# attention loop: persistent second ALiBi bias buffer (keys 32..63) taken as the MFMA C operand (D != C), both halves stepped once per tile
# speedup vs baseline: 1.0426x; 1.0082x over previous
.Ldyn_back:
.LBB0_310:
	s_cmp_lt_i32 s90, s82
	s_cselect_b64 s[4:5], -1, 0
	s_cmp_lt_u32 s90, 4
	s_cselect_b64 s[2:3], -1, 0
	s_mov_b64 s[12:13], -1
	s_and_b64 vcc, exec, s[2:3]
	s_cbranch_vccnz .LBB0_312
	s_waitcnt lgkmcnt(1)
	v_mfma_f32_32x32x16_bf16 v[130:145], v[158:161], v[166:169], v[2:17]
	s_and_b64 s[4:5], s[4:5], exec
	s_cselect_b32 s4, 0, s77
	s_sub_i32 s4, s90, s4
	s_add_i32 s4, s4, -4
	s_cmp_ge_i32 s4, s99
	s_cselect_b64 s[12:13], -1, 0
	s_not_b64 s[4:5], s[12:13]
	v_mfma_f32_32x32x16_bf16 v[114:129], v[150:153], v[166:169], v[228:243]
	v_max3_f32 v246, v98, v97, v105
	v_exp_f32_e32 v246, v246
	s_waitcnt lgkmcnt(0)
	v_mfma_f32_32x32x16_bf16 v[130:145], v[154:157], v[162:165], v[130:145]
	v_mul_f32_e32 v246, 0x4f800000, v246
	v_cmp_ge_f32_e32 vcc, v246, v175
	v_mfma_f32_32x32x16_bf16 v[114:129], v[146:149], v[162:165], v[114:129]
	s_mov_b64 s[80:81], -1
	s_cmp_lg_u64 s[4:5], 0
	s_cbranch_scc1 .LBB0_319
	s_cmp_eq_u32 s99, 0
	s_cbranch_scc1 .Lq_fullA
	s_cmp_lg_u64 vcc, 0
	s_cbranch_scc1 .LBB0_319
	s_branch .Lq_fullA

.LBB0_318:
	v_max_f32_e32 v147, v146, v146
	v_max_f32_e32 v147, 0, v147
	v_cndmask_b32_e64 v147, v147, v146, s[12:13]
	v_exp_f32_e64 v146, -v147
	v_add_f32_e32 v182, v182, v147
	v_sub_f32_e32 v113, v113, v147
	v_sub_f32_e32 v112, v112, v147
	v_cndmask_b32_e64 v146, v146, 1.0, s[12:13]
	v_pk_mul_f32 v[174:175], v[174:175], v[146:147] op_sel_hi:[1,0]
	v_sub_f32_e32 v111, v111, v147
	v_sub_f32_e32 v110, v110, v147
	v_sub_f32_e32 v109, v109, v147
	v_sub_f32_e32 v108, v108, v147
	v_sub_f32_e32 v107, v107, v147
	v_sub_f32_e32 v106, v106, v147
	v_sub_f32_e32 v105, v105, v147
	v_sub_f32_e32 v104, v104, v147
	v_sub_f32_e32 v103, v103, v147
	v_sub_f32_e32 v102, v102, v147
	v_sub_f32_e32 v101, v101, v147
	v_sub_f32_e32 v100, v100, v147
	v_sub_f32_e32 v99, v99, v147
	v_sub_f32_e32 v98, v98, v147
	v_sub_f32_e32 v97, v97, v147
	v_sub_f32_e32 v96, v96, v147
	v_sub_f32_e32 v95, v95, v147
	v_sub_f32_e32 v94, v94, v147
	v_sub_f32_e32 v93, v93, v147
	v_sub_f32_e32 v92, v92, v147
	v_sub_f32_e32 v91, v91, v147
	v_sub_f32_e32 v90, v90, v147
	v_sub_f32_e32 v89, v89, v147
	v_sub_f32_e32 v88, v88, v147
	v_sub_f32_e32 v87, v87, v147
	v_sub_f32_e32 v86, v86, v147
	v_sub_f32_e32 v85, v85, v147
	v_sub_f32_e32 v84, v84, v147
	v_sub_f32_e32 v83, v83, v147
	v_sub_f32_e32 v82, v82, v147
	v_sub_f32_e32 v17, v17, v147
	v_sub_f32_e32 v16, v16, v147
	v_sub_f32_e32 v15, v15, v147
	v_sub_f32_e32 v14, v14, v147
	v_sub_f32_e32 v13, v13, v147
	v_sub_f32_e32 v12, v12, v147
	v_sub_f32_e32 v11, v11, v147
	v_sub_f32_e32 v10, v10, v147
	v_sub_f32_e32 v9, v9, v147
	v_sub_f32_e32 v8, v8, v147
	v_sub_f32_e32 v7, v7, v147
	v_sub_f32_e32 v6, v6, v147
	v_sub_f32_e32 v5, v5, v147
	v_sub_f32_e32 v4, v4, v147
	v_sub_f32_e32 v3, v3, v147
	v_sub_f32_e32 v2, v2, v147
	v_sub_f32_e32 v243, v243, v147
	v_sub_f32_e32 v242, v242, v147
	v_sub_f32_e32 v241, v241, v147
	v_sub_f32_e32 v240, v240, v147
	v_sub_f32_e32 v239, v239, v147
	v_sub_f32_e32 v238, v238, v147
	v_sub_f32_e32 v237, v237, v147
	v_sub_f32_e32 v236, v236, v147
	v_sub_f32_e32 v235, v235, v147
	v_sub_f32_e32 v234, v234, v147
	v_sub_f32_e32 v233, v233, v147
	v_sub_f32_e32 v232, v232, v147
	v_sub_f32_e32 v231, v231, v147
	v_sub_f32_e32 v230, v230, v147
	v_sub_f32_e32 v229, v229, v147
	v_sub_f32_e32 v228, v228, v147
	v_sub_f32_e32 v145, v145, v147
	v_sub_f32_e32 v144, v144, v147
	v_sub_f32_e32 v143, v143, v147
	v_sub_f32_e32 v142, v142, v147
	v_sub_f32_e32 v141, v141, v147
	v_sub_f32_e32 v140, v140, v147
	v_sub_f32_e32 v139, v139, v147
	v_sub_f32_e32 v138, v138, v147
	v_sub_f32_e32 v137, v137, v147
	v_sub_f32_e32 v136, v136, v147
	v_sub_f32_e32 v135, v135, v147
	v_sub_f32_e32 v134, v134, v147
	v_sub_f32_e32 v133, v133, v147
	v_sub_f32_e32 v132, v132, v147
	v_sub_f32_e32 v131, v131, v147
	v_sub_f32_e32 v130, v130, v147
	v_sub_f32_e32 v129, v129, v147
	v_sub_f32_e32 v128, v128, v147
	v_sub_f32_e32 v127, v127, v147
	v_sub_f32_e32 v126, v126, v147
	v_sub_f32_e32 v125, v125, v147
	v_sub_f32_e32 v124, v124, v147
	v_sub_f32_e32 v123, v123, v147
	v_sub_f32_e32 v122, v122, v147
	v_sub_f32_e32 v121, v121, v147
	v_sub_f32_e32 v120, v120, v147
	v_sub_f32_e32 v119, v119, v147
	v_sub_f32_e32 v118, v118, v147
	v_sub_f32_e32 v117, v117, v147
	v_sub_f32_e32 v116, v116, v147
	v_sub_f32_e32 v115, v115, v147
	v_sub_f32_e32 v114, v114, v147
	v_pk_mul_f32 v[64:65], v[64:65], v[146:147] op_sel_hi:[1,0]
	v_pk_mul_f32 v[62:63], v[62:63], v[146:147] op_sel_hi:[1,0]
	v_pk_mul_f32 v[60:61], v[60:61], v[146:147] op_sel_hi:[1,0]
	v_pk_mul_f32 v[58:59], v[58:59], v[146:147] op_sel_hi:[1,0]
	v_pk_mul_f32 v[56:57], v[56:57], v[146:147] op_sel_hi:[1,0]
	v_pk_mul_f32 v[54:55], v[54:55], v[146:147] op_sel_hi:[1,0]
	v_pk_mul_f32 v[52:53], v[52:53], v[146:147] op_sel_hi:[1,0]
	v_pk_mul_f32 v[50:51], v[50:51], v[146:147] op_sel_hi:[1,0]
	v_pk_mul_f32 v[32:33], v[32:33], v[146:147] op_sel_hi:[1,0]
	v_pk_mul_f32 v[30:31], v[30:31], v[146:147] op_sel_hi:[1,0]
	v_pk_mul_f32 v[28:29], v[28:29], v[146:147] op_sel_hi:[1,0]
	v_pk_mul_f32 v[26:27], v[26:27], v[146:147] op_sel_hi:[1,0]
	v_pk_mul_f32 v[24:25], v[24:25], v[146:147] op_sel_hi:[1,0]
	v_pk_mul_f32 v[22:23], v[22:23], v[146:147] op_sel_hi:[1,0]
	v_pk_mul_f32 v[20:21], v[20:21], v[146:147] op_sel_hi:[1,0]
	v_pk_mul_f32 v[18:19], v[18:19], v[146:147] op_sel_hi:[1,0]
	v_pk_mul_f32 v[80:81], v[80:81], v[146:147] op_sel_hi:[1,0]
	v_pk_mul_f32 v[78:79], v[78:79], v[146:147] op_sel_hi:[1,0]
	v_pk_mul_f32 v[76:77], v[76:77], v[146:147] op_sel_hi:[1,0]
	v_pk_mul_f32 v[74:75], v[74:75], v[146:147] op_sel_hi:[1,0]
	v_pk_mul_f32 v[72:73], v[72:73], v[146:147] op_sel_hi:[1,0]
	v_pk_mul_f32 v[70:71], v[70:71], v[146:147] op_sel_hi:[1,0]
	v_pk_mul_f32 v[68:69], v[68:69], v[146:147] op_sel_hi:[1,0]
	v_pk_mul_f32 v[66:67], v[66:67], v[146:147] op_sel_hi:[1,0]
	v_pk_mul_f32 v[48:49], v[48:49], v[146:147] op_sel_hi:[1,0]
	v_pk_mul_f32 v[46:47], v[46:47], v[146:147] op_sel_hi:[1,0]
	v_pk_mul_f32 v[44:45], v[44:45], v[146:147] op_sel_hi:[1,0]
	v_pk_mul_f32 v[42:43], v[42:43], v[146:147] op_sel_hi:[1,0]
	v_pk_mul_f32 v[40:41], v[40:41], v[146:147] op_sel_hi:[1,0]
	v_pk_mul_f32 v[38:39], v[38:39], v[146:147] op_sel_hi:[1,0]
	v_pk_mul_f32 v[36:37], v[36:37], v[146:147] op_sel_hi:[1,0]
	v_pk_mul_f32 v[34:35], v[34:35], v[146:147] op_sel_hi:[1,0]

.Ldma_done:
	s_cmp_eq_u32 s87, s90
	s_cselect_b64 s[12:13], -1, 0
	s_or_b64 s[12:13], s[2:3], s[12:13]
	s_mov_b64 s[2:3], -1
	s_cbranch_scc1 .Lb_nform
	s_add_i32 s100, s88, 0x4000
	s_and_b32 s100, s100, 0xffff
	v_add_u32_e32 v82, s100, v186
	ds_read_b128 v[162:165], v82
	ds_read_b128 v[150:153], v82 offset:4096
	v_add_u32_e32 v82, s100, v188
	ds_read_b128 v[154:157], v82
	ds_read_b128 v[146:149], v82 offset:4096
	ds_read_b128 v[166:169], v189
	ds_read_b128 v[158:161], v192
	v_sub_f32_e32 v17, v17, v173
	v_sub_f32_e32 v16, v16, v173
	v_sub_f32_e32 v15, v15, v173
	v_sub_f32_e32 v14, v14, v173
	v_sub_f32_e32 v13, v13, v173
	v_sub_f32_e32 v12, v12, v173
	v_sub_f32_e32 v11, v11, v173
	v_sub_f32_e32 v10, v10, v173
	v_sub_f32_e32 v9, v9, v173
	v_sub_f32_e32 v8, v8, v173
	v_sub_f32_e32 v7, v7, v173
	v_sub_f32_e32 v6, v6, v173
	v_sub_f32_e32 v5, v5, v173
	v_sub_f32_e32 v4, v4, v173
	v_sub_f32_e32 v3, v3, v173
	v_sub_f32_e32 v2, v2, v173
	v_sub_f32_e32 v243, v243, v173
	v_sub_f32_e32 v242, v242, v173
	v_sub_f32_e32 v241, v241, v173
	v_sub_f32_e32 v240, v240, v173
	v_sub_f32_e32 v239, v239, v173
	v_sub_f32_e32 v238, v238, v173
	v_sub_f32_e32 v237, v237, v173
	v_sub_f32_e32 v236, v236, v173
	v_sub_f32_e32 v235, v235, v173
	v_sub_f32_e32 v234, v234, v173
	v_sub_f32_e32 v233, v233, v173
	v_sub_f32_e32 v232, v232, v173
	v_sub_f32_e32 v231, v231, v173
	v_sub_f32_e32 v230, v230, v173
	v_sub_f32_e32 v229, v229, v173
	v_sub_f32_e32 v228, v228, v173
	s_add_i32 s12, s90, 1
	s_add_i32 s2, s88, 0x4000
	s_and_b32 s88, s2, 0xffff
	s_cmp_ge_i32 s12, s83
	s_cbranch_scc1 .LBB0_339
	s_cmp_lt_u32 s90, 3
	s_mov_b64 s[2:3], -1
	s_cbranch_scc1 .LBB0_336
	s_waitcnt lgkmcnt(1)
	v_mfma_f32_32x32x16_bf16 v[98:113], v[162:165], v[166:169], v[2:17]
	v_max3_f32 v246, v130, v129, v137
	v_exp_f32_e32 v246, v246
	v_mfma_f32_32x32x16_bf16 v[82:97], v[150:153], v[166:169], v[228:243]
	s_waitcnt lgkmcnt(0)
	v_mfma_f32_32x32x16_bf16 v[98:113], v[154:157], v[158:161], v[98:113]
	v_mul_f32_e32 v246, 0x4f800000, v246
	v_cmp_ge_f32_e32 vcc, v246, v174
	v_mfma_f32_32x32x16_bf16 v[82:97], v[146:149], v[158:161], v[82:97]
	s_mov_b64 s[2:3], -1
	s_cmp_lg_u64 s[4:5], 0
	s_cbranch_scc1 .LBB0_345
	s_cmp_lt_u32 s90, 4
	s_cbranch_scc1 .Lq_fullB
	s_cmp_eq_u32 s99, 0
	s_cbranch_scc1 .Lq_fullB
	s_cmp_lg_u64 vcc, 0
	s_cbranch_scc1 .LBB0_345
	s_branch .Lq_fullB

.Lqk_B_noreads:
	s_cmp_lt_u32 s90, 3
	s_mov_b64 s[2:3], -1
	s_cbranch_scc1 .LBB0_336
	s_waitcnt lgkmcnt(1)
	v_mfma_f32_32x32x16_bf16 v[98:113], v[162:165], v[166:169], v[2:17]
	s_cmp_lt_i32 s12, s82
	s_cselect_b64 vcc, -1, 0
	v_cndmask_b32_e32 v246, v197, v196, vcc
	v_pk_add_f32 v[242:243], v[246:247], v[16:17] op_sel_hi:[0,1]
	v_pk_add_f32 v[240:241], v[246:247], v[14:15] op_sel_hi:[0,1]
	v_pk_add_f32 v[238:239], v[246:247], v[12:13] op_sel_hi:[0,1]
	v_pk_add_f32 v[236:237], v[246:247], v[10:11] op_sel_hi:[0,1]
	v_pk_add_f32 v[234:235], v[246:247], v[8:9] op_sel_hi:[0,1]
	v_pk_add_f32 v[232:233], v[246:247], v[6:7] op_sel_hi:[0,1]
	v_pk_add_f32 v[230:231], v[246:247], v[4:5] op_sel_hi:[0,1]
	v_pk_add_f32 v[228:229], v[246:247], v[2:3] op_sel_hi:[0,1]
	s_nop 1
	v_mfma_f32_32x32x16_bf16 v[82:97], v[150:153], v[166:169], v[228:243]
	s_waitcnt lgkmcnt(0)
	v_mfma_f32_32x32x16_bf16 v[98:113], v[154:157], v[158:161], v[98:113]
	v_mfma_f32_32x32x16_bf16 v[82:97], v[146:149], v[158:161], v[82:97]
	s_branch .LBB0_339

.Lq_fullB:
	v_max_f32_e32 v148, v132, v116
	v_max3_f32 v146, v130, v114, v134
	v_max3_f32 v149, v133, v117, v137
	v_max3_f32 v148, v148, v136, v120
	v_max3_f32 v147, v131, v115, v135
	v_max3_f32 v146, v146, v118, v138
	v_max3_f32 v149, v149, v121, v141
	v_max3_f32 v148, v148, v140, v124
	v_max3_f32 v147, v147, v119, v139
	v_max3_f32 v146, v146, v122, v142
	v_max3_f32 v149, v149, v125, v145
	v_max3_f32 v148, v148, v144, v128
	v_max3_f32 v147, v147, v123, v143
	v_max3_f32 v146, v146, v126, v127
	v_max3_f32 v148, v148, v129, v149
	v_max3_f32 v146, v146, v147, v148
	v_mov_b32_e32 v147, v146
	s_nop 1
	v_permlane32_swap_b32_e32 v146, v147
	s_nop 0
	v_max_f32_e32 v146, v146, v147
	v_exp_f32_e32 v147, v146
	v_cmp_lt_f32_e32 vcc, s20, v146
	v_mul_f32_e32 v147, 0x4f800000, v147
	v_cmp_ge_f32_e64 s[4:5], v147, v174
	s_cbranch_vccz .LBB0_344
	v_max_f32_e32 v146, v146, v146
	v_max_f32_e32 v147, 0, v146
	v_exp_f32_e64 v146, -v147
	v_add_f32_e32 v182, v182, v147
	v_sub_f32_e32 v145, v145, v147
	v_sub_f32_e32 v144, v144, v147
	v_pk_mul_f32 v[174:175], v[174:175], v[146:147] op_sel_hi:[1,0]
	v_sub_f32_e32 v143, v143, v147
	v_sub_f32_e32 v142, v142, v147
	v_sub_f32_e32 v141, v141, v147
	v_sub_f32_e32 v140, v140, v147
	v_sub_f32_e32 v139, v139, v147
	v_sub_f32_e32 v138, v138, v147
	v_sub_f32_e32 v137, v137, v147
	v_sub_f32_e32 v136, v136, v147
	v_sub_f32_e32 v135, v135, v147
	v_sub_f32_e32 v134, v134, v147
	v_sub_f32_e32 v133, v133, v147
	v_sub_f32_e32 v132, v132, v147
	v_sub_f32_e32 v131, v131, v147
	v_sub_f32_e32 v130, v130, v147
	v_sub_f32_e32 v129, v129, v147
	v_sub_f32_e32 v128, v128, v147
	v_sub_f32_e32 v127, v127, v147
	v_sub_f32_e32 v126, v126, v147
	v_sub_f32_e32 v125, v125, v147
	v_sub_f32_e32 v124, v124, v147
	v_sub_f32_e32 v123, v123, v147
	v_sub_f32_e32 v122, v122, v147
	v_sub_f32_e32 v121, v121, v147
	v_sub_f32_e32 v120, v120, v147
	v_sub_f32_e32 v119, v119, v147
	v_sub_f32_e32 v118, v118, v147
	v_sub_f32_e32 v117, v117, v147
	v_sub_f32_e32 v116, v116, v147
	v_sub_f32_e32 v115, v115, v147
	v_sub_f32_e32 v114, v114, v147
	v_sub_f32_e32 v17, v17, v147
	v_sub_f32_e32 v16, v16, v147
	v_sub_f32_e32 v15, v15, v147
	v_sub_f32_e32 v14, v14, v147
	v_sub_f32_e32 v13, v13, v147
	v_sub_f32_e32 v12, v12, v147
	v_sub_f32_e32 v11, v11, v147
	v_sub_f32_e32 v10, v10, v147
	v_sub_f32_e32 v9, v9, v147
	v_sub_f32_e32 v8, v8, v147
	v_sub_f32_e32 v7, v7, v147
	v_sub_f32_e32 v6, v6, v147
	v_sub_f32_e32 v5, v5, v147
	v_sub_f32_e32 v4, v4, v147
	v_sub_f32_e32 v3, v3, v147
	v_sub_f32_e32 v2, v2, v147
	v_sub_f32_e32 v243, v243, v147
	v_sub_f32_e32 v242, v242, v147
	v_sub_f32_e32 v241, v241, v147
	v_sub_f32_e32 v240, v240, v147
	v_sub_f32_e32 v239, v239, v147
	v_sub_f32_e32 v238, v238, v147
	v_sub_f32_e32 v237, v237, v147
	v_sub_f32_e32 v236, v236, v147
	v_sub_f32_e32 v235, v235, v147
	v_sub_f32_e32 v234, v234, v147
	v_sub_f32_e32 v233, v233, v147
	v_sub_f32_e32 v232, v232, v147
	v_sub_f32_e32 v231, v231, v147
	v_sub_f32_e32 v230, v230, v147
	v_sub_f32_e32 v229, v229, v147
	v_sub_f32_e32 v228, v228, v147
	v_sub_f32_e32 v113, v113, v147
	v_sub_f32_e32 v112, v112, v147
	v_sub_f32_e32 v111, v111, v147
	v_sub_f32_e32 v110, v110, v147
	v_sub_f32_e32 v109, v109, v147
	v_sub_f32_e32 v108, v108, v147
	v_sub_f32_e32 v107, v107, v147
	v_sub_f32_e32 v106, v106, v147
	v_sub_f32_e32 v105, v105, v147
	v_sub_f32_e32 v104, v104, v147
	v_sub_f32_e32 v103, v103, v147
	v_sub_f32_e32 v102, v102, v147
	v_sub_f32_e32 v101, v101, v147
	v_sub_f32_e32 v100, v100, v147
	v_sub_f32_e32 v99, v99, v147
	v_sub_f32_e32 v98, v98, v147
	v_sub_f32_e32 v97, v97, v147
	v_sub_f32_e32 v96, v96, v147
	v_sub_f32_e32 v95, v95, v147
	v_sub_f32_e32 v94, v94, v147
	v_sub_f32_e32 v93, v93, v147
	v_sub_f32_e32 v92, v92, v147
	v_sub_f32_e32 v91, v91, v147
	v_sub_f32_e32 v90, v90, v147
	v_sub_f32_e32 v89, v89, v147
	v_sub_f32_e32 v88, v88, v147
	v_sub_f32_e32 v87, v87, v147
	v_sub_f32_e32 v86, v86, v147
	v_sub_f32_e32 v85, v85, v147
	v_sub_f32_e32 v84, v84, v147
	v_sub_f32_e32 v83, v83, v147
	v_sub_f32_e32 v82, v82, v147
	v_pk_mul_f32 v[64:65], v[64:65], v[146:147] op_sel_hi:[1,0]
	v_pk_mul_f32 v[62:63], v[62:63], v[146:147] op_sel_hi:[1,0]
	v_pk_mul_f32 v[60:61], v[60:61], v[146:147] op_sel_hi:[1,0]
	v_pk_mul_f32 v[58:59], v[58:59], v[146:147] op_sel_hi:[1,0]
	v_pk_mul_f32 v[56:57], v[56:57], v[146:147] op_sel_hi:[1,0]
	v_pk_mul_f32 v[54:55], v[54:55], v[146:147] op_sel_hi:[1,0]
	v_pk_mul_f32 v[52:53], v[52:53], v[146:147] op_sel_hi:[1,0]
	v_pk_mul_f32 v[50:51], v[50:51], v[146:147] op_sel_hi:[1,0]
	v_pk_mul_f32 v[32:33], v[32:33], v[146:147] op_sel_hi:[1,0]
	v_pk_mul_f32 v[30:31], v[30:31], v[146:147] op_sel_hi:[1,0]
	v_pk_mul_f32 v[28:29], v[28:29], v[146:147] op_sel_hi:[1,0]
	v_pk_mul_f32 v[26:27], v[26:27], v[146:147] op_sel_hi:[1,0]
	v_pk_mul_f32 v[24:25], v[24:25], v[146:147] op_sel_hi:[1,0]
	v_pk_mul_f32 v[22:23], v[22:23], v[146:147] op_sel_hi:[1,0]
	v_pk_mul_f32 v[20:21], v[20:21], v[146:147] op_sel_hi:[1,0]
	v_pk_mul_f32 v[18:19], v[18:19], v[146:147] op_sel_hi:[1,0]
	v_pk_mul_f32 v[80:81], v[80:81], v[146:147] op_sel_hi:[1,0]
	v_pk_mul_f32 v[78:79], v[78:79], v[146:147] op_sel_hi:[1,0]
	v_pk_mul_f32 v[76:77], v[76:77], v[146:147] op_sel_hi:[1,0]
	v_pk_mul_f32 v[74:75], v[74:75], v[146:147] op_sel_hi:[1,0]
	v_pk_mul_f32 v[72:73], v[72:73], v[146:147] op_sel_hi:[1,0]
	v_pk_mul_f32 v[70:71], v[70:71], v[146:147] op_sel_hi:[1,0]
	v_pk_mul_f32 v[68:69], v[68:69], v[146:147] op_sel_hi:[1,0]
	v_pk_mul_f32 v[66:67], v[66:67], v[146:147] op_sel_hi:[1,0]
	v_pk_mul_f32 v[48:49], v[48:49], v[146:147] op_sel_hi:[1,0]
	v_pk_mul_f32 v[46:47], v[46:47], v[146:147] op_sel_hi:[1,0]
	v_pk_mul_f32 v[44:45], v[44:45], v[146:147] op_sel_hi:[1,0]
	v_pk_mul_f32 v[42:43], v[42:43], v[146:147] op_sel_hi:[1,0]
	v_pk_mul_f32 v[40:41], v[40:41], v[146:147] op_sel_hi:[1,0]
	v_pk_mul_f32 v[38:39], v[38:39], v[146:147] op_sel_hi:[1,0]
	v_pk_mul_f32 v[36:37], v[36:37], v[146:147] op_sel_hi:[1,0]
	v_pk_mul_f32 v[34:35], v[34:35], v[146:147] op_sel_hi:[1,0]

.LBB0_349:
	v_mov_b32_e32 v228, 0x2000
	v_mov_b32_e32 v229, 0x7000
	v_mov_b32_e32 v230, 1
	v_mov_b32_e32 v231, 0x3f4ccccd
	v_mov_b32_e32 v232, 0x260
	v_mov_b32_e32 v233, 0x3727c5ac
	v_mov_b32_e32 v234, 0x7f800000
	v_mov_b32_e32 v235, 0x3fb8aa3b
	v_mov_b32_e32 v236, 0xa0
	v_mov_b32_e32 v237, 0xa1
	v_mov_b32_e32 v238, 0x7fc00000
	v_readlane_b32 s87, v244, 26
	s_movk_i32 s88, 0x600
	v_readlane_b32 s89, v244, 21
	s_mov_b32 s90, 0x46000000
	s_branch .LBB0_351
